# EpiGLU epilogue: YS row loads of rows 1-6 of each column half issued together ahead of use (fragment registers), vmcnt re-derived
# baseline (speedup 1.0000x reference)
; __device__ __forceinline__ unsigned cvt_pk_bf16(float lo, float hi) { unsigned r; asm volatile("v_cvt_pk_bf16_f32 %0, %1, %2" : "=v"(r) : "v"(lo), "v"(hi)); return r; }
; __device__ __forceinline__ float sigmoidf_(float x) { return __builtin_amdgcn_rcpf(1.0f + __expf(-x)); }
;     __device__ __forceinline__ void operator()(const f32x4 (&acc)[2][2][4][2], const Unit& u, int wr, int wc, int fr, int fq) const {
;     ...
;         for (int bj = 0; bj < 2; ++bj) {
;             const int c = col0 + bj * 128;
;             const f32x4 b0 = *(const f32x4*)(bglu + c), b1 = *(const f32x4*)(bglu + c + 4);
; #pragma unroll
;             for (int ai = 0; ai < 2; ++ai)
; #pragma unroll
;                 for (int m = 0; m < 4; ++m) {
;                     const int row = row0 + ai * 128 + m * 16;
;                     const f32x4 y0 = *(const f32x4*)(YS + (size_t)row * 512 + c), y1 = *(const f32x4*)(YS + (size_t)row * 512 + c + 4);
;                     const f32x4 a0 = acc[ai][bj][m][0] + b0, a1 = acc[ai][bj][m][1] + b1;
;                     float o[8];
; #pragma unroll
;                     for (int j = 0; j < 4; ++j) { o[j] = y0[j] * sigmoidf_(a0[j]); o[4 + j] = y1[j] * sigmoidf_(a1[j]); }
;                     u32x4 w; w.x = cvt_pk_bf16(o[0], o[1]); w.y = cvt_pk_bf16(o[2], o[3]); w.z = cvt_pk_bf16(o[4], o[5]); w.w = cvt_pk_bf16(o[6], o[7]);
;                     *(u32x4*)(YCAT + (size_t)row * DM + 1536 + c) = w;
.LBB0_117:
	v_lshl_or_b32 v158, s33, 8, v169
	v_ashrrev_i32_e32 v159, 31, v158
	v_lshlrev_b64 v[160:161], 2, v[158:159]
	v_lshl_add_u64 v[154:155], s[18:19], 0, v[160:161]
	global_load_dwordx4 v[80:83], v[154:155], off offset:16
	global_load_dwordx4 v[84:87], v[154:155], off
	v_lshl_add_u32 v162, s34, 8, v167
	v_ashrrev_i32_e32 v163, 31, v162
	v_readlane_b32 s36, v251, 44
	v_lshlrev_b64 v[138:139], 11, v[162:163]
	v_readlane_b32 s37, v251, 45
	v_readlane_b32 s34, v251, 12
	v_readlane_b32 s35, v251, 13
	v_lshl_add_u64 v[138:139], s[36:37], 0, v[138:139]
	v_lshl_add_u64 v[156:157], v[138:139], 0, v[160:161]
	global_load_dwordx4 v[138:141], v[156:157], off offset:16
	global_load_dwordx4 v[172:175], v[156:157], off
	v_add_co_u32_e32 v180, vcc, 0x8000, v156
	s_nop 1
	v_addc_co_u32_e32 v181, vcc, 0, v157, vcc
	global_load_dwordx4 v[202:205], v[180:181], off offset:16
	global_load_dwordx4 v[206:209], v[180:181], off
	v_add_co_u32_e32 v180, vcc, 0x10000, v156
	s_nop 1
	v_addc_co_u32_e32 v181, vcc, 0, v157, vcc
	global_load_dwordx4 v[210:213], v[180:181], off offset:16
	global_load_dwordx4 v[214:217], v[180:181], off
	v_add_co_u32_e32 v180, vcc, 0x18000, v156
	s_nop 1
	v_addc_co_u32_e32 v181, vcc, 0, v157, vcc
	global_load_dwordx4 v[218:221], v[180:181], off offset:16
	global_load_dwordx4 v[222:225], v[180:181], off
	v_add_co_u32_e32 v180, vcc, 0x40000, v156
	s_nop 1
	v_addc_co_u32_e32 v181, vcc, 0, v157, vcc
	global_load_dwordx4 v[226:229], v[180:181], off offset:16
	global_load_dwordx4 v[230:233], v[180:181], off
	v_add_co_u32_e32 v180, vcc, 0x48000, v156
	s_nop 1
	v_addc_co_u32_e32 v181, vcc, 0, v157, vcc
	global_load_dwordx4 v[234:237], v[180:181], off offset:16
	global_load_dwordx4 v[238:241], v[180:181], off
	v_add_co_u32_e32 v180, vcc, 0x50000, v156
	s_nop 1
	v_addc_co_u32_e32 v181, vcc, 0, v157, vcc
	global_load_dwordx4 v[242:245], v[180:181], off offset:16
	global_load_dwordx4 v[176:179], v[180:181], off
	v_lshlrev_b64 v[158:159], 1, v[158:159]
	v_or_b32_e32 v164, 16, v162
	v_ashrrev_i32_e32 v165, 31, v164
	s_andn2_b64 vcc, exec, s[30:31]
	s_waitcnt vmcnt(15)
	v_add_f32_e32 v128, v128, v80
	v_add_f32_e32 v129, v129, v81
	v_add_f32_e32 v130, v130, v82
	v_mul_f32_e32 v128, 0xbfb8aa3b, v128
	v_mul_f32_e32 v129, 0xbfb8aa3b, v129
	v_mul_f32_e32 v130, 0xbfb8aa3b, v130
	v_exp_f32_e32 v128, v128
	v_exp_f32_e32 v129, v129
	v_exp_f32_e32 v130, v130
	s_waitcnt vmcnt(14)
	v_add_f32_e32 v132, v132, v84
	v_add_f32_e32 v128, 1.0, v128
	v_add_f32_e32 v129, 1.0, v129
	v_add_f32_e32 v130, 1.0, v130
	v_rcp_f32_e32 v128, v128
	v_rcp_f32_e32 v129, v129
	v_rcp_f32_e32 v130, v130
	v_mul_f32_e32 v132, 0xbfb8aa3b, v132
	s_waitcnt vmcnt(13)
	v_mul_f32_e32 v138, v138, v128
	v_add_f32_e32 v128, v133, v85
	v_mul_f32_e32 v133, v139, v129
	v_add_f32_e32 v129, v134, v86
	v_mul_f32_e32 v134, v140, v130
	v_add_f32_e32 v130, v135, v87
	v_mul_f32_e32 v128, 0xbfb8aa3b, v128
	v_mul_f32_e32 v129, 0xbfb8aa3b, v129
	v_mul_f32_e32 v130, 0xbfb8aa3b, v130
	v_exp_f32_e32 v132, v132
	v_exp_f32_e32 v128, v128
	v_exp_f32_e32 v129, v129
	v_exp_f32_e32 v130, v130
	v_add_f32_e32 v131, v131, v83
	v_mul_f32_e32 v131, 0xbfb8aa3b, v131
	v_exp_f32_e32 v131, v131
	v_add_f32_e32 v132, 1.0, v132
	v_add_f32_e32 v128, 1.0, v128
	v_add_f32_e32 v129, 1.0, v129
	v_add_f32_e32 v130, 1.0, v130
	v_rcp_f32_e32 v132, v132
	v_rcp_f32_e32 v128, v128
	v_rcp_f32_e32 v129, v129
	v_rcp_f32_e32 v130, v130
	v_add_f32_e32 v131, 1.0, v131
	v_rcp_f32_e32 v131, v131
	s_waitcnt vmcnt(12)
	v_mul_f32_e32 v132, v172, v132
	v_mul_f32_e32 v128, v173, v128
	v_mul_f32_e32 v129, v174, v129
	v_mul_f32_e32 v130, v175, v130
	v_cvt_pk_bf16_f32 v128, v132, v128
	v_cvt_pk_bf16_f32 v129, v129, v130
	v_cvt_pk_bf16_f32 v130, v138, v133
	v_lshlrev_b64 v[132:133], 12, v[162:163]
	v_lshl_add_u64 v[132:133], s[34:35], 0, v[132:133]
	v_mul_f32_e32 v131, v141, v131
	v_lshl_add_u64 v[132:133], v[132:133], 0, v[158:159]
	v_cvt_pk_bf16_f32 v131, v134, v131
	global_store_dwordx4 v[132:133], v[128:131], off offset:3072
	v_add_f32_e32 v120, v120, v80
	v_add_f32_e32 v121, v121, v81
	v_lshlrev_b64 v[128:129], 11, v[164:165]
	v_lshl_add_u64 v[128:129], s[36:37], 0, v[128:129]
	v_lshl_add_u64 v[134:135], v[128:129], 0, v[160:161]
	v_add_f32_e32 v122, v122, v82
	v_mul_f32_e32 v120, 0xbfb8aa3b, v120
	v_mul_f32_e32 v121, 0xbfb8aa3b, v121
	v_mul_f32_e32 v122, 0xbfb8aa3b, v122
	v_exp_f32_e32 v120, v120
	v_exp_f32_e32 v121, v121
	v_exp_f32_e32 v122, v122
	v_add_f32_e32 v124, v124, v84
	v_add_f32_e32 v120, 1.0, v120
	v_add_f32_e32 v121, 1.0, v121
	v_add_f32_e32 v122, 1.0, v122
	v_rcp_f32_e32 v120, v120
	v_rcp_f32_e32 v121, v121
	v_rcp_f32_e32 v122, v122
	v_mul_f32_e32 v124, 0xbfb8aa3b, v124
	v_exp_f32_e32 v124, v124
	v_add_f32_e32 v123, v123, v83
	v_mul_f32_e32 v123, 0xbfb8aa3b, v123
	v_exp_f32_e32 v123, v123
	v_add_f32_e32 v124, 1.0, v124
	v_rcp_f32_e32 v124, v124
	v_add_f32_e32 v112, v112, v80
	v_add_f32_e32 v123, 1.0, v123
	v_rcp_f32_e32 v123, v123
	v_add_f32_e32 v113, v113, v81
	v_add_f32_e32 v114, v114, v82
	v_mul_f32_e32 v112, 0xbfb8aa3b, v112
	v_mul_f32_e32 v113, 0xbfb8aa3b, v113
	v_mul_f32_e32 v114, 0xbfb8aa3b, v114
	v_exp_f32_e32 v112, v112
	v_exp_f32_e32 v113, v113
	v_exp_f32_e32 v114, v114
	v_add_f32_e32 v116, v116, v84
	v_add_f32_e32 v112, 1.0, v112
	v_add_f32_e32 v113, 1.0, v113
	v_add_f32_e32 v114, 1.0, v114
	v_rcp_f32_e32 v112, v112
	v_rcp_f32_e32 v113, v113
	v_rcp_f32_e32 v114, v114
	v_mul_f32_e32 v116, 0xbfb8aa3b, v116
	v_exp_f32_e32 v116, v116
	v_add_f32_e32 v115, v115, v83
	v_mul_f32_e32 v115, 0xbfb8aa3b, v115
	v_exp_f32_e32 v115, v115
	v_add_f32_e32 v116, 1.0, v116
	v_rcp_f32_e32 v116, v116
	v_add_f32_e32 v104, v104, v80
	v_add_f32_e32 v115, 1.0, v115
	v_rcp_f32_e32 v115, v115
	v_add_f32_e32 v105, v105, v81
	v_add_f32_e32 v106, v106, v82
	v_mul_f32_e32 v104, 0xbfb8aa3b, v104
	v_mul_f32_e32 v105, 0xbfb8aa3b, v105
	v_mul_f32_e32 v106, 0xbfb8aa3b, v106
	v_exp_f32_e32 v104, v104
	v_exp_f32_e32 v105, v105
	v_exp_f32_e32 v106, v106
	v_add_f32_e32 v108, v108, v84
	v_add_f32_e32 v104, 1.0, v104
	v_add_f32_e32 v105, 1.0, v105
	v_add_f32_e32 v106, 1.0, v106
	v_rcp_f32_e32 v104, v104
	v_rcp_f32_e32 v105, v105
	v_rcp_f32_e32 v106, v106
	v_mul_f32_e32 v108, 0xbfb8aa3b, v108
	v_exp_f32_e32 v108, v108
	v_add_f32_e32 v107, v107, v83
	v_mul_f32_e32 v107, 0xbfb8aa3b, v107
	v_exp_f32_e32 v107, v107
	v_add_f32_e32 v108, 1.0, v108
	v_rcp_f32_e32 v108, v108
	v_add_f32_e32 v96, v96, v80
	v_add_f32_e32 v107, 1.0, v107
	v_rcp_f32_e32 v107, v107
	v_add_f32_e32 v97, v97, v81
	v_add_f32_e32 v98, v98, v82
	v_mul_f32_e32 v96, 0xbfb8aa3b, v96
	v_mul_f32_e32 v97, 0xbfb8aa3b, v97
	s_waitcnt vmcnt(12)
; __device__ __forceinline__ unsigned cvt_pk_bf16(float lo, float hi) { unsigned r; asm volatile("v_cvt_pk_bf16_f32 %0, %1, %2" : "=v"(r) : "v"(lo), "v"(hi)); return r; }
; __device__ __forceinline__ float sigmoidf_(float x) { return __builtin_amdgcn_rcpf(1.0f + __expf(-x)); }
;     __device__ __forceinline__ void operator()(const f32x4 (&acc)[2][2][4][2], const Unit& u, int wr, int wc, int fr, int fq) const {
;     ...
;             const int c = col0 + bj * 128;
;             const f32x4 b0 = *(const f32x4*)(bglu + c), b1 = *(const f32x4*)(bglu + c + 4);
; #pragma unroll
;             for (int ai = 0; ai < 2; ++ai)
; #pragma unroll
;                 for (int m = 0; m < 4; ++m) {
;                     const int row = row0 + ai * 128 + m * 16;
;                     const f32x4 y0 = *(const f32x4*)(YS + (size_t)row * 512 + c), y1 = *(const f32x4*)(YS + (size_t)row * 512 + c + 4);
;                     const f32x4 a0 = acc[ai][bj][m][0] + b0, a1 = acc[ai][bj][m][1] + b1;
;                     float o[8];
; #pragma unroll
;                     for (int j = 0; j < 4; ++j) { o[j] = y0[j] * sigmoidf_(a0[j]); o[4 + j] = y1[j] * sigmoidf_(a1[j]); }
;                     u32x4 w; w.x = cvt_pk_bf16(o[0], o[1]); w.y = cvt_pk_bf16(o[2], o[3]); w.z = cvt_pk_bf16(o[4], o[5]); w.w = cvt_pk_bf16(o[6], o[7]);
;                     *(u32x4*)(YCAT + (size_t)row * DM + 1536 + c) = w;
	v_mul_f32_e32 v128, v120, v202
	v_add_f32_e32 v120, v125, v85
	v_mul_f32_e32 v125, v121, v203
	v_add_f32_e32 v121, v126, v86
	v_mul_f32_e32 v126, v122, v204
	v_add_f32_e32 v122, v127, v87
	v_mul_f32_e32 v120, 0xbfb8aa3b, v120
	v_mul_f32_e32 v121, 0xbfb8aa3b, v121
	v_mul_f32_e32 v122, 0xbfb8aa3b, v122
	v_exp_f32_e32 v120, v120
	v_exp_f32_e32 v121, v121
	v_exp_f32_e32 v122, v122
	s_waitcnt vmcnt(11)
	v_mul_f32_e32 v124, v124, v206
	v_add_f32_e32 v120, 1.0, v120
	v_add_f32_e32 v121, 1.0, v121
	v_add_f32_e32 v122, 1.0, v122
	v_rcp_f32_e32 v120, v120
	v_rcp_f32_e32 v121, v121
	v_rcp_f32_e32 v122, v122
	v_mul_f32_e32 v123, v123, v205
	v_mul_f32_e32 v120, v120, v207
	v_mul_f32_e32 v121, v121, v208
	v_mul_f32_e32 v122, v122, v209
	v_cvt_pk_bf16_f32 v120, v124, v120
	v_cvt_pk_bf16_f32 v121, v121, v122
	v_cvt_pk_bf16_f32 v122, v128, v125
	v_lshlrev_b64 v[124:125], 12, v[164:165]
	v_lshl_add_u64 v[124:125], s[34:35], 0, v[124:125]
	v_or_b32_e32 v128, 32, v162
	v_lshl_add_u64 v[124:125], v[124:125], 0, v[158:159]
	v_ashrrev_i32_e32 v129, 31, v128
	v_cvt_pk_bf16_f32 v123, v126, v123
	global_store_dwordx4 v[124:125], v[120:123], off offset:3072
	v_mul_f32_e32 v98, 0xbfb8aa3b, v98
	v_exp_f32_e32 v96, v96
	v_lshlrev_b64 v[120:121], 11, v[128:129]
	v_lshl_add_u64 v[120:121], s[36:37], 0, v[120:121]
	v_lshl_add_u64 v[126:127], v[120:121], 0, v[160:161]
	v_exp_f32_e32 v97, v97
	v_exp_f32_e32 v98, v98
	v_add_f32_e32 v96, 1.0, v96
	v_rcp_f32_e32 v96, v96
	v_add_f32_e32 v97, 1.0, v97
	v_add_f32_e32 v98, 1.0, v98
	v_rcp_f32_e32 v97, v97
	v_rcp_f32_e32 v98, v98
	v_add_f32_e32 v100, v100, v84
	v_mul_f32_e32 v100, 0xbfb8aa3b, v100
	v_exp_f32_e32 v100, v100
	v_add_f32_e32 v99, v99, v83
	v_mul_f32_e32 v99, 0xbfb8aa3b, v99
	v_exp_f32_e32 v99, v99
	v_add_f32_e32 v100, 1.0, v100
	v_rcp_f32_e32 v100, v100
	v_add_f32_e32 v88, v88, v80
	v_add_f32_e32 v99, 1.0, v99
	v_rcp_f32_e32 v99, v99
	v_add_f32_e32 v89, v89, v81
	v_add_f32_e32 v90, v90, v82
	v_mul_f32_e32 v88, 0xbfb8aa3b, v88
	v_mul_f32_e32 v89, 0xbfb8aa3b, v89
	v_mul_f32_e32 v90, 0xbfb8aa3b, v90
	v_exp_f32_e32 v88, v88
	v_exp_f32_e32 v89, v89
	v_exp_f32_e32 v90, v90
	v_add_f32_e32 v92, v92, v84
	v_add_f32_e32 v88, 1.0, v88
	v_add_f32_e32 v89, 1.0, v89
	v_add_f32_e32 v90, 1.0, v90
	v_rcp_f32_e32 v88, v88
	v_rcp_f32_e32 v89, v89
	v_rcp_f32_e32 v90, v90
	v_mul_f32_e32 v92, 0xbfb8aa3b, v92
	v_exp_f32_e32 v92, v92
	v_add_f32_e32 v91, v91, v83
	v_mul_f32_e32 v91, 0xbfb8aa3b, v91
	v_exp_f32_e32 v91, v91
	v_add_f32_e32 v92, 1.0, v92
	v_rcp_f32_e32 v92, v92
	v_add_f32_e32 v72, v72, v80
	v_add_f32_e32 v91, 1.0, v91
	v_rcp_f32_e32 v91, v91
	v_add_f32_e32 v73, v73, v81
	v_add_f32_e32 v74, v74, v82
	v_mul_f32_e32 v72, 0xbfb8aa3b, v72
	v_mul_f32_e32 v73, 0xbfb8aa3b, v73
	v_mul_f32_e32 v74, 0xbfb8aa3b, v74
	v_exp_f32_e32 v72, v72
	v_exp_f32_e32 v73, v73
	v_exp_f32_e32 v74, v74
	v_add_f32_e32 v76, v76, v84
	v_add_f32_e32 v72, 1.0, v72
	v_add_f32_e32 v73, 1.0, v73
	v_add_f32_e32 v74, 1.0, v74
	v_rcp_f32_e32 v72, v72
	v_rcp_f32_e32 v73, v73
	v_rcp_f32_e32 v74, v74
	v_mul_f32_e32 v76, 0xbfb8aa3b, v76
	v_exp_f32_e32 v76, v76
	v_add_f32_e32 v75, v75, v83
	v_mul_f32_e32 v75, 0xbfb8aa3b, v75
	v_exp_f32_e32 v75, v75
	v_add_f32_e32 v76, 1.0, v76
	v_rcp_f32_e32 v76, v76
	v_add_f32_e32 v64, v64, v80
	v_add_f32_e32 v75, 1.0, v75
	v_rcp_f32_e32 v75, v75
	v_add_f32_e32 v65, v65, v81
	v_add_f32_e32 v66, v66, v82
	v_mul_f32_e32 v64, 0xbfb8aa3b, v64
	v_mul_f32_e32 v65, 0xbfb8aa3b, v65
	v_mul_f32_e32 v66, 0xbfb8aa3b, v66
	v_exp_f32_e32 v64, v64
	v_exp_f32_e32 v65, v65
	v_exp_f32_e32 v66, v66
	v_add_f32_e32 v68, v68, v84
	s_waitcnt vmcnt(11)
	v_mul_f32_e32 v120, v112, v210
	v_add_f32_e32 v112, v117, v85
	v_mul_f32_e32 v117, v113, v211
	v_add_f32_e32 v113, v118, v86
	v_mul_f32_e32 v118, v114, v212
	v_add_f32_e32 v114, v119, v87
	v_mul_f32_e32 v112, 0xbfb8aa3b, v112
	v_mul_f32_e32 v113, 0xbfb8aa3b, v113
	v_mul_f32_e32 v114, 0xbfb8aa3b, v114
	v_exp_f32_e32 v112, v112
	v_exp_f32_e32 v113, v113
	v_exp_f32_e32 v114, v114
	s_waitcnt vmcnt(10)
	v_mul_f32_e32 v116, v116, v214
	v_add_f32_e32 v112, 1.0, v112
	v_add_f32_e32 v113, 1.0, v113
	v_add_f32_e32 v114, 1.0, v114
	v_rcp_f32_e32 v112, v112
	v_rcp_f32_e32 v113, v113
	v_rcp_f32_e32 v114, v114
	v_mul_f32_e32 v115, v115, v213
	v_mul_f32_e32 v112, v112, v215
	v_mul_f32_e32 v113, v113, v216
	v_mul_f32_e32 v114, v114, v217
	v_cvt_pk_bf16_f32 v112, v116, v112
	v_cvt_pk_bf16_f32 v113, v113, v114
	v_cvt_pk_bf16_f32 v114, v120, v117
	v_lshlrev_b64 v[116:117], 12, v[128:129]
	v_lshl_add_u64 v[116:117], s[34:35], 0, v[116:117]
	v_or_b32_e32 v120, 48, v162
	v_lshl_add_u64 v[116:117], v[116:117], 0, v[158:159]
	v_ashrrev_i32_e32 v121, 31, v120
	v_cvt_pk_bf16_f32 v115, v118, v115
	global_store_dwordx4 v[116:117], v[112:115], off offset:3072
	v_add_f32_e32 v64, 1.0, v64
	v_add_f32_e32 v65, 1.0, v65
	v_lshlrev_b64 v[112:113], 11, v[120:121]
	v_lshl_add_u64 v[112:113], s[36:37], 0, v[112:113]
	v_lshl_add_u64 v[118:119], v[112:113], 0, v[160:161]
	v_add_f32_e32 v66, 1.0, v66
	v_rcp_f32_e32 v64, v64
	v_rcp_f32_e32 v65, v65
	v_rcp_f32_e32 v66, v66
	v_mul_f32_e32 v68, 0xbfb8aa3b, v68
	v_exp_f32_e32 v68, v68
	v_add_f32_e32 v67, v67, v83
	v_mul_f32_e32 v67, 0xbfb8aa3b, v67
	v_exp_f32_e32 v67, v67
	v_add_f32_e32 v68, 1.0, v68
	v_rcp_f32_e32 v68, v68
	v_add_f32_e32 v67, 1.0, v67
	v_rcp_f32_e32 v67, v67
	s_waitcnt vmcnt(10)
	v_mul_f32_e32 v112, v104, v218
	v_add_f32_e32 v104, v109, v85
	v_mul_f32_e32 v109, v105, v219
	v_add_f32_e32 v105, v110, v86
	v_mul_f32_e32 v110, v106, v220
	v_add_f32_e32 v106, v111, v87
	v_mul_f32_e32 v104, 0xbfb8aa3b, v104
	v_mul_f32_e32 v105, 0xbfb8aa3b, v105
	v_mul_f32_e32 v106, 0xbfb8aa3b, v106
	v_exp_f32_e32 v104, v104
	v_exp_f32_e32 v105, v105
	v_exp_f32_e32 v106, v106
	s_waitcnt vmcnt(9)
; __device__ __forceinline__ unsigned cvt_pk_bf16(float lo, float hi) { unsigned r; asm volatile("v_cvt_pk_bf16_f32 %0, %1, %2" : "=v"(r) : "v"(lo), "v"(hi)); return r; }
; __device__ __forceinline__ float sigmoidf_(float x) { return __builtin_amdgcn_rcpf(1.0f + __expf(-x)); }
;     __device__ __forceinline__ void operator()(const f32x4 (&acc)[2][2][4][2], const Unit& u, int wr, int wc, int fr, int fq) const {
;     ...
;             const int c = col0 + bj * 128;
;             const f32x4 b0 = *(const f32x4*)(bglu + c), b1 = *(const f32x4*)(bglu + c + 4);
; #pragma unroll
;             for (int ai = 0; ai < 2; ++ai)
; #pragma unroll
;                 for (int m = 0; m < 4; ++m) {
;                     const int row = row0 + ai * 128 + m * 16;
;                     const f32x4 y0 = *(const f32x4*)(YS + (size_t)row * 512 + c), y1 = *(const f32x4*)(YS + (size_t)row * 512 + c + 4);
;                     const f32x4 a0 = acc[ai][bj][m][0] + b0, a1 = acc[ai][bj][m][1] + b1;
;                     float o[8];
; #pragma unroll
;                     for (int j = 0; j < 4; ++j) { o[j] = y0[j] * sigmoidf_(a0[j]); o[4 + j] = y1[j] * sigmoidf_(a1[j]); }
;                     u32x4 w; w.x = cvt_pk_bf16(o[0], o[1]); w.y = cvt_pk_bf16(o[2], o[3]); w.z = cvt_pk_bf16(o[4], o[5]); w.w = cvt_pk_bf16(o[6], o[7]);
;                     *(u32x4*)(YCAT + (size_t)row * DM + 1536 + c) = w;
	v_mul_f32_e32 v108, v108, v222
	v_add_f32_e32 v104, 1.0, v104
	v_add_f32_e32 v105, 1.0, v105
	v_add_f32_e32 v106, 1.0, v106
	v_rcp_f32_e32 v104, v104
	v_rcp_f32_e32 v105, v105
	v_rcp_f32_e32 v106, v106
	v_mul_f32_e32 v107, v107, v221
	v_mul_f32_e32 v104, v104, v223
	v_mul_f32_e32 v105, v105, v224
	v_mul_f32_e32 v106, v106, v225
	v_cvt_pk_bf16_f32 v104, v108, v104
	v_cvt_pk_bf16_f32 v105, v105, v106
	v_cvt_pk_bf16_f32 v106, v112, v109
	v_lshlrev_b64 v[108:109], 12, v[120:121]
	v_lshl_add_u64 v[108:109], s[34:35], 0, v[108:109]
	v_add_u32_e32 v112, 0x80, v162
	v_lshl_add_u64 v[108:109], v[108:109], 0, v[158:159]
	v_ashrrev_i32_e32 v113, 31, v112
	v_cvt_pk_bf16_f32 v107, v110, v107
	global_store_dwordx4 v[108:109], v[104:107], off offset:3072
	s_nop 1
	v_lshlrev_b64 v[104:105], 11, v[112:113]
	v_lshl_add_u64 v[104:105], s[36:37], 0, v[104:105]
	v_lshl_add_u64 v[110:111], v[104:105], 0, v[160:161]
	s_waitcnt vmcnt(9)
	v_mul_f32_e32 v104, v96, v226
	v_add_f32_e32 v96, v101, v85
	v_mul_f32_e32 v101, v97, v227
	v_add_f32_e32 v97, v102, v86
	v_mul_f32_e32 v102, v98, v228
	v_add_f32_e32 v98, v103, v87
	v_mul_f32_e32 v96, 0xbfb8aa3b, v96
	v_mul_f32_e32 v97, 0xbfb8aa3b, v97
	v_mul_f32_e32 v98, 0xbfb8aa3b, v98
	v_exp_f32_e32 v96, v96
	v_exp_f32_e32 v97, v97
	v_exp_f32_e32 v98, v98
	s_waitcnt vmcnt(8)
	v_mul_f32_e32 v100, v100, v230
	v_add_f32_e32 v96, 1.0, v96
	v_add_f32_e32 v97, 1.0, v97
	v_add_f32_e32 v98, 1.0, v98
	v_rcp_f32_e32 v96, v96
	v_rcp_f32_e32 v97, v97
	v_rcp_f32_e32 v98, v98
	v_mul_f32_e32 v99, v99, v229
	v_mul_f32_e32 v96, v96, v231
	v_mul_f32_e32 v97, v97, v232
	v_mul_f32_e32 v98, v98, v233
	v_cvt_pk_bf16_f32 v96, v100, v96
	v_cvt_pk_bf16_f32 v97, v97, v98
	v_cvt_pk_bf16_f32 v98, v104, v101
	v_lshlrev_b64 v[100:101], 12, v[112:113]
	v_lshl_add_u64 v[100:101], s[34:35], 0, v[100:101]
	v_add_u32_e32 v104, 0x90, v162
	v_lshl_add_u64 v[100:101], v[100:101], 0, v[158:159]
	v_ashrrev_i32_e32 v105, 31, v104
	v_cvt_pk_bf16_f32 v99, v102, v99
	global_store_dwordx4 v[100:101], v[96:99], off offset:3072
	s_nop 1
	v_lshlrev_b64 v[96:97], 11, v[104:105]
	v_lshl_add_u64 v[96:97], s[36:37], 0, v[96:97]
	v_lshl_add_u64 v[102:103], v[96:97], 0, v[160:161]
	s_waitcnt vmcnt(8)
	v_mul_f32_e32 v96, v88, v234
	v_add_f32_e32 v88, v93, v85
	v_mul_f32_e32 v93, v89, v235
	v_add_f32_e32 v89, v94, v86
	v_mul_f32_e32 v94, v90, v236
	v_add_f32_e32 v90, v95, v87
	v_mul_f32_e32 v88, 0xbfb8aa3b, v88
	v_mul_f32_e32 v89, 0xbfb8aa3b, v89
	v_mul_f32_e32 v90, 0xbfb8aa3b, v90
	v_exp_f32_e32 v88, v88
	v_exp_f32_e32 v89, v89
	v_exp_f32_e32 v90, v90
	s_waitcnt vmcnt(7)
	v_mul_f32_e32 v92, v92, v238
	v_add_f32_e32 v88, 1.0, v88
	v_add_f32_e32 v89, 1.0, v89
	v_add_f32_e32 v90, 1.0, v90
	v_rcp_f32_e32 v88, v88
	v_rcp_f32_e32 v89, v89
	v_rcp_f32_e32 v90, v90
	v_mul_f32_e32 v91, v91, v237
	v_mul_f32_e32 v88, v88, v239
	v_mul_f32_e32 v89, v89, v240
	v_mul_f32_e32 v90, v90, v241
	v_cvt_pk_bf16_f32 v88, v92, v88
	v_cvt_pk_bf16_f32 v89, v89, v90
	v_cvt_pk_bf16_f32 v90, v96, v93
	v_lshlrev_b64 v[92:93], 12, v[104:105]
	v_lshl_add_u64 v[92:93], s[34:35], 0, v[92:93]
	v_add_u32_e32 v96, 0xa0, v162
	v_lshl_add_u64 v[92:93], v[92:93], 0, v[158:159]
	v_ashrrev_i32_e32 v97, 31, v96
	v_cvt_pk_bf16_f32 v91, v94, v91
	global_store_dwordx4 v[92:93], v[88:91], off offset:3072
	s_nop 1
	v_lshlrev_b64 v[88:89], 11, v[96:97]
	v_lshl_add_u64 v[88:89], s[36:37], 0, v[88:89]
	v_lshl_add_u64 v[94:95], v[88:89], 0, v[160:161]
	s_waitcnt vmcnt(7)
	v_mul_f32_e32 v88, v72, v242
	v_add_f32_e32 v72, v77, v85
	v_mul_f32_e32 v77, v73, v243
	v_add_f32_e32 v73, v78, v86
	v_mul_f32_e32 v78, v74, v244
	v_add_f32_e32 v74, v79, v87
	v_mul_f32_e32 v72, 0xbfb8aa3b, v72
	v_mul_f32_e32 v73, 0xbfb8aa3b, v73
	v_mul_f32_e32 v74, 0xbfb8aa3b, v74
	v_exp_f32_e32 v72, v72
	v_exp_f32_e32 v73, v73
	v_exp_f32_e32 v74, v74
	s_waitcnt vmcnt(6)
	v_mul_f32_e32 v76, v76, v176
	v_add_f32_e32 v72, 1.0, v72
	v_add_f32_e32 v73, 1.0, v73
	v_add_f32_e32 v74, 1.0, v74
	v_rcp_f32_e32 v72, v72
	v_rcp_f32_e32 v73, v73
	v_rcp_f32_e32 v74, v74
	v_mul_f32_e32 v75, v75, v245
	v_mul_f32_e32 v72, v72, v177
	v_mul_f32_e32 v73, v73, v178
	v_mul_f32_e32 v74, v74, v179
	v_cvt_pk_bf16_f32 v72, v76, v72
	v_cvt_pk_bf16_f32 v73, v73, v74
	v_cvt_pk_bf16_f32 v74, v88, v77
	v_lshlrev_b64 v[76:77], 12, v[96:97]
	v_lshl_add_u64 v[76:77], s[34:35], 0, v[76:77]
	v_add_u32_e32 v88, 0xb0, v162
	v_lshl_add_u64 v[76:77], v[76:77], 0, v[158:159]
	v_ashrrev_i32_e32 v89, 31, v88
	v_cvt_pk_bf16_f32 v75, v78, v75
	global_store_dwordx4 v[76:77], v[72:75], off offset:3072
	s_nop 1
	v_lshlrev_b64 v[72:73], 11, v[88:89]
	v_lshl_add_u64 v[72:73], s[36:37], 0, v[72:73]
	v_lshl_add_u64 v[78:79], v[72:73], 0, v[160:161]
	global_load_dwordx4 v[72:75], v[78:79], off offset:16
	global_load_dwordx4 v[96:99], v[78:79], off
	s_waitcnt vmcnt(1)
	v_mul_f32_e32 v72, v64, v72
	v_add_f32_e32 v64, v69, v85
	v_mul_f32_e32 v69, v65, v73
	v_add_f32_e32 v65, v70, v86
	v_mul_f32_e32 v70, v66, v74
	v_add_f32_e32 v66, v71, v87
	v_mul_f32_e32 v64, 0xbfb8aa3b, v64
	v_mul_f32_e32 v65, 0xbfb8aa3b, v65
	v_mul_f32_e32 v66, 0xbfb8aa3b, v66
	v_exp_f32_e32 v64, v64
	v_exp_f32_e32 v65, v65
	v_exp_f32_e32 v66, v66
	s_waitcnt vmcnt(0)
; __device__ __forceinline__ unsigned cvt_pk_bf16(float lo, float hi) { unsigned r; asm volatile("v_cvt_pk_bf16_f32 %0, %1, %2" : "=v"(r) : "v"(lo), "v"(hi)); return r; }
; __device__ __forceinline__ float sigmoidf_(float x) { return __builtin_amdgcn_rcpf(1.0f + __expf(-x)); }
;     __device__ __forceinline__ void operator()(const f32x4 (&acc)[2][2][4][2], const Unit& u, int wr, int wc, int fr, int fq) const {
;     ...
;             const f32x4 b0 = *(const f32x4*)(bglu + c), b1 = *(const f32x4*)(bglu + c + 4);
; #pragma unroll
;             for (int ai = 0; ai < 2; ++ai)
; #pragma unroll
;                 for (int m = 0; m < 4; ++m) {
;                     const int row = row0 + ai * 128 + m * 16;
;                     const f32x4 y0 = *(const f32x4*)(YS + (size_t)row * 512 + c), y1 = *(const f32x4*)(YS + (size_t)row * 512 + c + 4);
;                     const f32x4 a0 = acc[ai][bj][m][0] + b0, a1 = acc[ai][bj][m][1] + b1;
;                     float o[8];
; #pragma unroll
;                     for (int j = 0; j < 4; ++j) { o[j] = y0[j] * sigmoidf_(a0[j]); o[4 + j] = y1[j] * sigmoidf_(a1[j]); }
;                     u32x4 w; w.x = cvt_pk_bf16(o[0], o[1]); w.y = cvt_pk_bf16(o[2], o[3]); w.z = cvt_pk_bf16(o[4], o[5]); w.w = cvt_pk_bf16(o[6], o[7]);
;                     *(u32x4*)(YCAT + (size_t)row * DM + 1536 + c) = w;
	v_mul_f32_e32 v68, v68, v96
	v_add_f32_e32 v64, 1.0, v64
	v_add_f32_e32 v65, 1.0, v65
	v_add_f32_e32 v66, 1.0, v66
	v_rcp_f32_e32 v64, v64
	v_rcp_f32_e32 v65, v65
	v_rcp_f32_e32 v66, v66
	v_mul_f32_e32 v67, v67, v75
	v_mul_f32_e32 v64, v64, v97
	v_mul_f32_e32 v65, v65, v98
	v_mul_f32_e32 v66, v66, v99
	v_cvt_pk_bf16_f32 v64, v68, v64
	v_cvt_pk_bf16_f32 v65, v65, v66
	v_cvt_pk_bf16_f32 v66, v72, v69
	v_lshlrev_b64 v[68:69], 12, v[88:89]
	v_lshl_add_u64 v[68:69], s[34:35], 0, v[68:69]
	v_lshl_add_u64 v[80:81], v[68:69], 0, v[158:159]
	v_cvt_pk_bf16_f32 v67, v70, v67
	global_store_dwordx4 v[80:81], v[64:67], off offset:3072
	global_load_dwordx4 v[64:67], v[154:155], off offset:528
	s_nop 0
	global_load_dwordx4 v[68:71], v[154:155], off offset:512
	global_load_dwordx4 v[72:75], v[156:157], off offset:528
	global_load_dwordx4 v[82:85], v[156:157], off offset:512
	global_load_dwordx4 v[202:205], v[134:135], off offset:528
	global_load_dwordx4 v[206:209], v[134:135], off offset:512
	global_load_dwordx4 v[210:213], v[126:127], off offset:528
	global_load_dwordx4 v[214:217], v[126:127], off offset:512
	global_load_dwordx4 v[218:221], v[118:119], off offset:528
	global_load_dwordx4 v[222:225], v[118:119], off offset:512
	global_load_dwordx4 v[226:229], v[110:111], off offset:528
	global_load_dwordx4 v[230:233], v[110:111], off offset:512
	global_load_dwordx4 v[234:237], v[102:103], off offset:528
	global_load_dwordx4 v[238:241], v[102:103], off offset:512
	global_load_dwordx4 v[242:245], v[94:95], off offset:528
	global_load_dwordx4 v[176:179], v[94:95], off offset:512
	s_mov_b64 s[34:35], -1
	s_waitcnt vmcnt(15)
	v_add_f32_e32 v56, v56, v64
	v_add_f32_e32 v57, v57, v65
	v_add_f32_e32 v58, v58, v66
	v_mul_f32_e32 v56, 0xbfb8aa3b, v56
	v_mul_f32_e32 v57, 0xbfb8aa3b, v57
	v_mul_f32_e32 v58, 0xbfb8aa3b, v58
	v_exp_f32_e32 v56, v56
	v_exp_f32_e32 v57, v57
	v_exp_f32_e32 v58, v58
	v_add_f32_e32 v59, v59, v67
	v_add_f32_e32 v56, 1.0, v56
	v_add_f32_e32 v57, 1.0, v57
	v_add_f32_e32 v58, 1.0, v58
	v_rcp_f32_e32 v56, v56
	v_rcp_f32_e32 v57, v57
	v_rcp_f32_e32 v58, v58
	s_waitcnt vmcnt(14)
	v_add_f32_e32 v60, v60, v68
	s_waitcnt vmcnt(13)
	v_mul_f32_e32 v72, v72, v56
	v_add_f32_e32 v56, v61, v69
	v_mul_f32_e32 v61, v73, v57
	v_add_f32_e32 v57, v62, v70
	v_mul_f32_e32 v62, v74, v58
	v_add_f32_e32 v58, v63, v71
	v_mul_f32_e32 v56, 0xbfb8aa3b, v56
	v_mul_f32_e32 v57, 0xbfb8aa3b, v57
	v_mul_f32_e32 v58, 0xbfb8aa3b, v58
	v_mul_f32_e32 v59, 0xbfb8aa3b, v59
	v_mul_f32_e32 v60, 0xbfb8aa3b, v60
	v_exp_f32_e32 v56, v56
	v_exp_f32_e32 v57, v57
	v_exp_f32_e32 v58, v58
	v_exp_f32_e32 v59, v59
	v_exp_f32_e32 v60, v60
	v_add_f32_e32 v56, 1.0, v56
	v_add_f32_e32 v57, 1.0, v57
	v_add_f32_e32 v58, 1.0, v58
	v_add_f32_e32 v59, 1.0, v59
	v_add_f32_e32 v60, 1.0, v60
	v_rcp_f32_e32 v56, v56
	v_rcp_f32_e32 v57, v57
	v_rcp_f32_e32 v58, v58
	v_rcp_f32_e32 v59, v59
	v_rcp_f32_e32 v60, v60
	s_waitcnt vmcnt(12)
	v_mul_f32_e32 v56, v83, v56
	v_mul_f32_e32 v57, v84, v57
	v_mul_f32_e32 v58, v85, v58
	v_mul_f32_e32 v59, v75, v59
	v_mul_f32_e32 v60, v82, v60
	v_cvt_pk_bf16_f32 v56, v60, v56
	v_cvt_pk_bf16_f32 v57, v57, v58
	v_cvt_pk_bf16_f32 v58, v72, v61
	v_cvt_pk_bf16_f32 v59, v62, v59
	global_store_dwordx4 v[132:133], v[56:59], off offset:3328
	s_nop 0
	v_add_f32_e32 v48, v48, v64
	v_add_f32_e32 v49, v49, v65
	v_add_f32_e32 v50, v50, v66
	v_mul_f32_e32 v48, 0xbfb8aa3b, v48
	v_mul_f32_e32 v49, 0xbfb8aa3b, v49
	v_mul_f32_e32 v50, 0xbfb8aa3b, v50
	v_exp_f32_e32 v48, v48
	v_exp_f32_e32 v49, v49
	v_exp_f32_e32 v50, v50
	v_add_f32_e32 v51, v51, v67
	v_add_f32_e32 v48, 1.0, v48
	v_add_f32_e32 v49, 1.0, v49
	v_add_f32_e32 v50, 1.0, v50
	v_rcp_f32_e32 v48, v48
	v_rcp_f32_e32 v49, v49
	v_rcp_f32_e32 v50, v50
	v_add_f32_e32 v52, v52, v68
	v_mul_f32_e32 v51, 0xbfb8aa3b, v51
	v_mul_f32_e32 v52, 0xbfb8aa3b, v52
	v_exp_f32_e32 v51, v51
	v_exp_f32_e32 v52, v52
	v_add_f32_e32 v40, v40, v64
	v_add_f32_e32 v41, v41, v65
	v_add_f32_e32 v51, 1.0, v51
	v_add_f32_e32 v52, 1.0, v52
	v_rcp_f32_e32 v51, v51
	v_rcp_f32_e32 v52, v52
	v_add_f32_e32 v42, v42, v66
	v_mul_f32_e32 v40, 0xbfb8aa3b, v40
	v_mul_f32_e32 v41, 0xbfb8aa3b, v41
	v_mul_f32_e32 v42, 0xbfb8aa3b, v42
	v_exp_f32_e32 v40, v40
	v_exp_f32_e32 v41, v41
	v_exp_f32_e32 v42, v42
	v_add_f32_e32 v43, v43, v67
	v_add_f32_e32 v40, 1.0, v40
	v_add_f32_e32 v41, 1.0, v41
	v_add_f32_e32 v42, 1.0, v42
	v_rcp_f32_e32 v40, v40
	v_rcp_f32_e32 v41, v41
	v_rcp_f32_e32 v42, v42
	v_add_f32_e32 v44, v44, v68
	v_mul_f32_e32 v43, 0xbfb8aa3b, v43
	v_mul_f32_e32 v44, 0xbfb8aa3b, v44
	v_exp_f32_e32 v43, v43
	v_exp_f32_e32 v44, v44
	v_add_f32_e32 v32, v32, v64
	v_add_f32_e32 v33, v33, v65
	v_add_f32_e32 v43, 1.0, v43
	v_add_f32_e32 v44, 1.0, v44
	v_rcp_f32_e32 v43, v43
	v_rcp_f32_e32 v44, v44
	v_add_f32_e32 v34, v34, v66
	v_mul_f32_e32 v32, 0xbfb8aa3b, v32
	v_mul_f32_e32 v33, 0xbfb8aa3b, v33
	v_mul_f32_e32 v34, 0xbfb8aa3b, v34
	v_exp_f32_e32 v32, v32
	v_exp_f32_e32 v33, v33
	v_exp_f32_e32 v34, v34
	v_add_f32_e32 v35, v35, v67
	v_add_f32_e32 v32, 1.0, v32
	v_add_f32_e32 v33, 1.0, v33
	v_add_f32_e32 v34, 1.0, v34
	v_rcp_f32_e32 v32, v32
	v_rcp_f32_e32 v33, v33
	v_rcp_f32_e32 v34, v34
	v_add_f32_e32 v36, v36, v68
	v_mul_f32_e32 v35, 0xbfb8aa3b, v35
	v_mul_f32_e32 v36, 0xbfb8aa3b, v36
	v_exp_f32_e32 v35, v35
	v_exp_f32_e32 v36, v36
	v_add_f32_e32 v24, v24, v64
	v_add_f32_e32 v25, v25, v65
	v_add_f32_e32 v35, 1.0, v35
	v_add_f32_e32 v36, 1.0, v36
	v_rcp_f32_e32 v35, v35
	v_rcp_f32_e32 v36, v36
	v_add_f32_e32 v26, v26, v66
	s_waitcnt vmcnt(12)
; __device__ __forceinline__ unsigned cvt_pk_bf16(float lo, float hi) { unsigned r; asm volatile("v_cvt_pk_bf16_f32 %0, %1, %2" : "=v"(r) : "v"(lo), "v"(hi)); return r; }
; __device__ __forceinline__ float sigmoidf_(float x) { return __builtin_amdgcn_rcpf(1.0f + __expf(-x)); }
;     __device__ __forceinline__ void operator()(const f32x4 (&acc)[2][2][4][2], const Unit& u, int wr, int wc, int fr, int fq) const {
;     ...
;             const f32x4 b0 = *(const f32x4*)(bglu + c), b1 = *(const f32x4*)(bglu + c + 4);
; #pragma unroll
;             for (int ai = 0; ai < 2; ++ai)
; #pragma unroll
;                 for (int m = 0; m < 4; ++m) {
;                     const int row = row0 + ai * 128 + m * 16;
;                     const f32x4 y0 = *(const f32x4*)(YS + (size_t)row * 512 + c), y1 = *(const f32x4*)(YS + (size_t)row * 512 + c + 4);
;                     const f32x4 a0 = acc[ai][bj][m][0] + b0, a1 = acc[ai][bj][m][1] + b1;
;                     float o[8];
; #pragma unroll
;                     for (int j = 0; j < 4; ++j) { o[j] = y0[j] * sigmoidf_(a0[j]); o[4 + j] = y1[j] * sigmoidf_(a1[j]); }
;                     u32x4 w; w.x = cvt_pk_bf16(o[0], o[1]); w.y = cvt_pk_bf16(o[2], o[3]); w.z = cvt_pk_bf16(o[4], o[5]); w.w = cvt_pk_bf16(o[6], o[7]);
;                     *(u32x4*)(YCAT + (size_t)row * DM + 1536 + c) = w;
	v_mul_f32_e32 v56, v48, v202
	v_add_f32_e32 v48, v53, v69
	v_mul_f32_e32 v53, v49, v203
	v_add_f32_e32 v49, v54, v70
	v_mul_f32_e32 v54, v50, v204
	v_add_f32_e32 v50, v55, v71
	v_mul_f32_e32 v48, 0xbfb8aa3b, v48
	v_mul_f32_e32 v49, 0xbfb8aa3b, v49
	v_mul_f32_e32 v50, 0xbfb8aa3b, v50
	v_exp_f32_e32 v48, v48
	v_exp_f32_e32 v49, v49
	v_exp_f32_e32 v50, v50
	v_mul_f32_e32 v51, v51, v205
	v_add_f32_e32 v48, 1.0, v48
	v_add_f32_e32 v49, 1.0, v49
	v_add_f32_e32 v50, 1.0, v50
	v_rcp_f32_e32 v48, v48
	v_rcp_f32_e32 v49, v49
	v_rcp_f32_e32 v50, v50
	s_waitcnt vmcnt(11)
	v_mul_f32_e32 v52, v52, v206
	v_mul_f32_e32 v48, v48, v207
	v_mul_f32_e32 v49, v49, v208
	v_mul_f32_e32 v50, v50, v209
	v_cvt_pk_bf16_f32 v48, v52, v48
	v_cvt_pk_bf16_f32 v49, v49, v50
	v_cvt_pk_bf16_f32 v50, v56, v53
	v_cvt_pk_bf16_f32 v51, v54, v51
	global_store_dwordx4 v[124:125], v[48:51], off offset:3328
	s_nop 0
	v_mul_f32_e32 v24, 0xbfb8aa3b, v24
	v_mul_f32_e32 v25, 0xbfb8aa3b, v25
	v_mul_f32_e32 v26, 0xbfb8aa3b, v26
	v_exp_f32_e32 v24, v24
	v_exp_f32_e32 v25, v25
	v_exp_f32_e32 v26, v26
	v_add_f32_e32 v27, v27, v67
	v_add_f32_e32 v24, 1.0, v24
	v_add_f32_e32 v25, 1.0, v25
	v_add_f32_e32 v26, 1.0, v26
	v_rcp_f32_e32 v24, v24
	v_rcp_f32_e32 v25, v25
	v_rcp_f32_e32 v26, v26
	v_add_f32_e32 v28, v28, v68
	v_mul_f32_e32 v27, 0xbfb8aa3b, v27
	v_mul_f32_e32 v28, 0xbfb8aa3b, v28
	v_exp_f32_e32 v27, v27
	v_exp_f32_e32 v28, v28
	v_add_f32_e32 v16, v16, v64
	v_add_f32_e32 v17, v17, v65
	v_add_f32_e32 v27, 1.0, v27
	v_add_f32_e32 v28, 1.0, v28
	v_rcp_f32_e32 v27, v27
	v_rcp_f32_e32 v28, v28
	v_add_f32_e32 v18, v18, v66
	v_mul_f32_e32 v16, 0xbfb8aa3b, v16
	v_mul_f32_e32 v17, 0xbfb8aa3b, v17
	v_mul_f32_e32 v18, 0xbfb8aa3b, v18
	v_exp_f32_e32 v16, v16
	v_exp_f32_e32 v17, v17
	v_exp_f32_e32 v18, v18
	v_add_f32_e32 v19, v19, v67
	v_add_f32_e32 v16, 1.0, v16
	v_add_f32_e32 v17, 1.0, v17
	v_add_f32_e32 v18, 1.0, v18
	v_rcp_f32_e32 v16, v16
	v_rcp_f32_e32 v17, v17
	v_rcp_f32_e32 v18, v18
	v_add_f32_e32 v20, v20, v68
	v_mul_f32_e32 v19, 0xbfb8aa3b, v19
	v_mul_f32_e32 v20, 0xbfb8aa3b, v20
	v_exp_f32_e32 v19, v19
	v_exp_f32_e32 v20, v20
	v_add_f32_e32 v8, v8, v64
	v_add_f32_e32 v9, v9, v65
	v_add_f32_e32 v19, 1.0, v19
	v_add_f32_e32 v20, 1.0, v20
	v_rcp_f32_e32 v19, v19
	v_rcp_f32_e32 v20, v20
	v_add_f32_e32 v10, v10, v66
	v_mul_f32_e32 v8, 0xbfb8aa3b, v8
	v_mul_f32_e32 v9, 0xbfb8aa3b, v9
	v_mul_f32_e32 v10, 0xbfb8aa3b, v10
	v_exp_f32_e32 v8, v8
	v_exp_f32_e32 v9, v9
	v_exp_f32_e32 v10, v10
	v_add_f32_e32 v11, v11, v67
	v_add_f32_e32 v8, 1.0, v8
	v_add_f32_e32 v9, 1.0, v9
	v_add_f32_e32 v10, 1.0, v10
	v_rcp_f32_e32 v8, v8
	v_rcp_f32_e32 v9, v9
	v_rcp_f32_e32 v10, v10
	v_add_f32_e32 v12, v12, v68
	v_mul_f32_e32 v11, 0xbfb8aa3b, v11
	v_mul_f32_e32 v12, 0xbfb8aa3b, v12
	v_exp_f32_e32 v11, v11
	v_exp_f32_e32 v12, v12
	v_add_f32_e32 v0, v0, v64
	v_add_f32_e32 v1, v1, v65
	v_add_f32_e32 v11, 1.0, v11
	v_add_f32_e32 v12, 1.0, v12
	v_rcp_f32_e32 v11, v11
	v_rcp_f32_e32 v12, v12
	v_add_f32_e32 v2, v2, v66
	v_mul_f32_e32 v0, 0xbfb8aa3b, v0
	v_mul_f32_e32 v1, 0xbfb8aa3b, v1
	v_mul_f32_e32 v2, 0xbfb8aa3b, v2
	s_waitcnt vmcnt(11)
	v_mul_f32_e32 v48, v40, v210
	v_add_f32_e32 v40, v45, v69
	v_mul_f32_e32 v45, v41, v211
	v_add_f32_e32 v41, v46, v70
	v_mul_f32_e32 v46, v42, v212
	v_add_f32_e32 v42, v47, v71
	v_mul_f32_e32 v40, 0xbfb8aa3b, v40
	v_mul_f32_e32 v41, 0xbfb8aa3b, v41
	v_mul_f32_e32 v42, 0xbfb8aa3b, v42
	v_exp_f32_e32 v40, v40
	v_exp_f32_e32 v41, v41
	v_exp_f32_e32 v42, v42
	v_mul_f32_e32 v43, v43, v213
	v_add_f32_e32 v40, 1.0, v40
	v_add_f32_e32 v41, 1.0, v41
	v_add_f32_e32 v42, 1.0, v42
	v_rcp_f32_e32 v40, v40
	v_rcp_f32_e32 v41, v41
	v_rcp_f32_e32 v42, v42
	s_waitcnt vmcnt(10)
	v_mul_f32_e32 v44, v44, v214
	v_mul_f32_e32 v40, v40, v215
	v_mul_f32_e32 v41, v41, v216
	v_mul_f32_e32 v42, v42, v217
	v_cvt_pk_bf16_f32 v40, v44, v40
	v_cvt_pk_bf16_f32 v41, v41, v42
	v_cvt_pk_bf16_f32 v42, v48, v45
	v_cvt_pk_bf16_f32 v43, v46, v43
	global_store_dwordx4 v[116:117], v[40:43], off offset:3328
	s_nop 0
	v_exp_f32_e32 v0, v0
	v_exp_f32_e32 v1, v1
	v_exp_f32_e32 v2, v2
	v_add_f32_e32 v3, v3, v67
	v_add_f32_e32 v0, 1.0, v0
	v_add_f32_e32 v1, 1.0, v1
	v_add_f32_e32 v2, 1.0, v2
	v_rcp_f32_e32 v0, v0
	v_rcp_f32_e32 v1, v1
	v_rcp_f32_e32 v2, v2
	v_add_f32_e32 v4, v4, v68
	v_mul_f32_e32 v3, 0xbfb8aa3b, v3
	v_mul_f32_e32 v4, 0xbfb8aa3b, v4
	v_exp_f32_e32 v3, v3
	v_exp_f32_e32 v4, v4
	v_add_f32_e32 v3, 1.0, v3
	v_add_f32_e32 v4, 1.0, v4
	v_rcp_f32_e32 v3, v3
	v_rcp_f32_e32 v4, v4
	s_waitcnt vmcnt(10)
; __device__ __forceinline__ unsigned cvt_pk_bf16(float lo, float hi) { unsigned r; asm volatile("v_cvt_pk_bf16_f32 %0, %1, %2" : "=v"(r) : "v"(lo), "v"(hi)); return r; }
; __device__ __forceinline__ float sigmoidf_(float x) { return __builtin_amdgcn_rcpf(1.0f + __expf(-x)); }
;     __device__ __forceinline__ void operator()(const f32x4 (&acc)[2][2][4][2], const Unit& u, int wr, int wc, int fr, int fq) const {
;     ...
;         for (int bj = 0; bj < 2; ++bj) {
;             const int c = col0 + bj * 128;
;             const f32x4 b0 = *(const f32x4*)(bglu + c), b1 = *(const f32x4*)(bglu + c + 4);
; #pragma unroll
;             for (int ai = 0; ai < 2; ++ai)
; #pragma unroll
;                 for (int m = 0; m < 4; ++m) {
;                     const int row = row0 + ai * 128 + m * 16;
;                     const f32x4 y0 = *(const f32x4*)(YS + (size_t)row * 512 + c), y1 = *(const f32x4*)(YS + (size_t)row * 512 + c + 4);
;                     const f32x4 a0 = acc[ai][bj][m][0] + b0, a1 = acc[ai][bj][m][1] + b1;
;                     float o[8];
; #pragma unroll
;                     for (int j = 0; j < 4; ++j) { o[j] = y0[j] * sigmoidf_(a0[j]); o[4 + j] = y1[j] * sigmoidf_(a1[j]); }
;                     u32x4 w; w.x = cvt_pk_bf16(o[0], o[1]); w.y = cvt_pk_bf16(o[2], o[3]); w.z = cvt_pk_bf16(o[4], o[5]); w.w = cvt_pk_bf16(o[6], o[7]);
;                     *(u32x4*)(YCAT + (size_t)row * DM + 1536 + c) = w;
;                 }
	v_mul_f32_e32 v40, v32, v218
	v_add_f32_e32 v32, v37, v69
	v_mul_f32_e32 v37, v33, v219
	v_add_f32_e32 v33, v38, v70
	v_mul_f32_e32 v38, v34, v220
	v_add_f32_e32 v34, v39, v71
	v_mul_f32_e32 v32, 0xbfb8aa3b, v32
	v_mul_f32_e32 v33, 0xbfb8aa3b, v33
	v_mul_f32_e32 v34, 0xbfb8aa3b, v34
	v_exp_f32_e32 v32, v32
	v_exp_f32_e32 v33, v33
	v_exp_f32_e32 v34, v34
	v_mul_f32_e32 v35, v35, v221
	v_add_f32_e32 v32, 1.0, v32
	v_add_f32_e32 v33, 1.0, v33
	v_add_f32_e32 v34, 1.0, v34
	v_rcp_f32_e32 v32, v32
	v_rcp_f32_e32 v33, v33
	v_rcp_f32_e32 v34, v34
	s_waitcnt vmcnt(9)
	v_mul_f32_e32 v36, v36, v222
	v_mul_f32_e32 v32, v32, v223
	v_mul_f32_e32 v33, v33, v224
	v_mul_f32_e32 v34, v34, v225
	v_cvt_pk_bf16_f32 v32, v36, v32
	v_cvt_pk_bf16_f32 v33, v33, v34
	v_cvt_pk_bf16_f32 v34, v40, v37
	v_cvt_pk_bf16_f32 v35, v38, v35
	global_store_dwordx4 v[108:109], v[32:35], off offset:3328
	s_nop 0
	s_waitcnt vmcnt(9)
	v_mul_f32_e32 v32, v24, v226
	v_add_f32_e32 v24, v29, v69
	v_mul_f32_e32 v29, v25, v227
	v_add_f32_e32 v25, v30, v70
	v_mul_f32_e32 v30, v26, v228
	v_add_f32_e32 v26, v31, v71
	v_mul_f32_e32 v24, 0xbfb8aa3b, v24
	v_mul_f32_e32 v25, 0xbfb8aa3b, v25
	v_mul_f32_e32 v26, 0xbfb8aa3b, v26
	v_exp_f32_e32 v24, v24
	v_exp_f32_e32 v25, v25
	v_exp_f32_e32 v26, v26
	v_mul_f32_e32 v27, v27, v229
	v_add_f32_e32 v24, 1.0, v24
	v_add_f32_e32 v25, 1.0, v25
	v_add_f32_e32 v26, 1.0, v26
	v_rcp_f32_e32 v24, v24
	v_rcp_f32_e32 v25, v25
	v_rcp_f32_e32 v26, v26
	s_waitcnt vmcnt(8)
	v_mul_f32_e32 v28, v28, v230
	v_mul_f32_e32 v24, v24, v231
	v_mul_f32_e32 v25, v25, v232
	v_mul_f32_e32 v26, v26, v233
	v_cvt_pk_bf16_f32 v24, v28, v24
	v_cvt_pk_bf16_f32 v25, v25, v26
	v_cvt_pk_bf16_f32 v26, v32, v29
	v_cvt_pk_bf16_f32 v27, v30, v27
	global_store_dwordx4 v[100:101], v[24:27], off offset:3328
	s_nop 0
	s_waitcnt vmcnt(8)
	v_mul_f32_e32 v24, v16, v234
	v_add_f32_e32 v16, v21, v69
	v_mul_f32_e32 v21, v17, v235
	v_add_f32_e32 v17, v22, v70
	v_mul_f32_e32 v22, v18, v236
	v_add_f32_e32 v18, v23, v71
	v_mul_f32_e32 v16, 0xbfb8aa3b, v16
	v_mul_f32_e32 v17, 0xbfb8aa3b, v17
	v_mul_f32_e32 v18, 0xbfb8aa3b, v18
	v_exp_f32_e32 v16, v16
	v_exp_f32_e32 v17, v17
	v_exp_f32_e32 v18, v18
	v_mul_f32_e32 v19, v19, v237
	v_add_f32_e32 v16, 1.0, v16
	v_add_f32_e32 v17, 1.0, v17
	v_add_f32_e32 v18, 1.0, v18
	v_rcp_f32_e32 v16, v16
	v_rcp_f32_e32 v17, v17
	v_rcp_f32_e32 v18, v18
	s_waitcnt vmcnt(7)
	v_mul_f32_e32 v20, v20, v238
	v_mul_f32_e32 v16, v16, v239
	v_mul_f32_e32 v17, v17, v240
	v_mul_f32_e32 v18, v18, v241
	v_cvt_pk_bf16_f32 v16, v20, v16
	v_cvt_pk_bf16_f32 v17, v17, v18
	v_cvt_pk_bf16_f32 v18, v24, v21
	v_cvt_pk_bf16_f32 v19, v22, v19
	global_store_dwordx4 v[92:93], v[16:19], off offset:3328
	s_nop 0
	s_waitcnt vmcnt(7)
	v_mul_f32_e32 v16, v8, v242
	v_add_f32_e32 v8, v13, v69
	v_mul_f32_e32 v13, v9, v243
	v_add_f32_e32 v9, v14, v70
	v_mul_f32_e32 v14, v10, v244
	v_add_f32_e32 v10, v15, v71
	v_mul_f32_e32 v8, 0xbfb8aa3b, v8
	v_mul_f32_e32 v9, 0xbfb8aa3b, v9
	v_mul_f32_e32 v10, 0xbfb8aa3b, v10
	v_exp_f32_e32 v8, v8
	v_exp_f32_e32 v9, v9
	v_exp_f32_e32 v10, v10
	v_mul_f32_e32 v11, v11, v245
	v_add_f32_e32 v8, 1.0, v8
	v_add_f32_e32 v9, 1.0, v9
	v_add_f32_e32 v10, 1.0, v10
	v_rcp_f32_e32 v8, v8
	v_rcp_f32_e32 v9, v9
	v_rcp_f32_e32 v10, v10
	s_waitcnt vmcnt(6)
	v_mul_f32_e32 v12, v12, v176
	v_mul_f32_e32 v8, v8, v177
	v_mul_f32_e32 v9, v9, v178
	v_mul_f32_e32 v10, v10, v179
	v_cvt_pk_bf16_f32 v8, v12, v8
	v_cvt_pk_bf16_f32 v9, v9, v10
	v_cvt_pk_bf16_f32 v10, v16, v13
	v_cvt_pk_bf16_f32 v11, v14, v11
	global_store_dwordx4 v[76:77], v[8:11], off offset:3328
	global_load_dwordx4 v[8:11], v[78:79], off offset:528
	s_nop 0
	global_load_dwordx4 v[12:15], v[78:79], off offset:512
	s_waitcnt vmcnt(1)
	v_mul_f32_e32 v8, v0, v8
	v_add_f32_e32 v0, v5, v69
	v_mul_f32_e32 v5, v1, v9
	v_add_f32_e32 v1, v6, v70
	v_mul_f32_e32 v6, v2, v10
	v_add_f32_e32 v2, v7, v71
	v_mul_f32_e32 v0, 0xbfb8aa3b, v0
	v_mul_f32_e32 v1, 0xbfb8aa3b, v1
	v_mul_f32_e32 v2, 0xbfb8aa3b, v2
	v_exp_f32_e32 v0, v0
	v_exp_f32_e32 v1, v1
	v_exp_f32_e32 v2, v2
	v_mul_f32_e32 v3, v3, v11
	v_add_f32_e32 v0, 1.0, v0
	v_add_f32_e32 v1, 1.0, v1
	v_add_f32_e32 v2, 1.0, v2
	v_rcp_f32_e32 v0, v0
	v_rcp_f32_e32 v1, v1
	v_rcp_f32_e32 v2, v2
	s_waitcnt vmcnt(0)
	v_mul_f32_e32 v4, v4, v12
	v_mul_f32_e32 v0, v0, v13
	v_mul_f32_e32 v1, v1, v14
	v_mul_f32_e32 v2, v2, v15
	v_cvt_pk_bf16_f32 v0, v4, v0
	v_cvt_pk_bf16_f32 v1, v1, v2
	v_cvt_pk_bf16_f32 v2, v8, v5
	v_cvt_pk_bf16_f32 v3, v6, v3
	global_store_dwordx4 v[80:81], v[0:3], off offset:3328
	s_cbranch_vccnz .LBB0_106
	s_andn2_b64 vcc, exec, s[6:7]
	s_cbranch_vccnz .LBB0_105
	s_barrier
	s_branch .LBB0_105
